# out-proj K-loop mid-point rescale (both layers): two row groups' partial-sum loads kept in flight in dead fragment registers, counted waits, instead of 8 serialized load-wait-compute steps
# speedup vs baseline: 1.0076x; 1.0037x over previous
.LBB0_858:
	s_cmpk_lg_i32 s62, 0x800
	s_cbranch_scc1 .LBB0_857
	v_mov_b32_e32 v3, v0
	s_mov_b32 s8, 0x358637bd
	v_and_or_b32 v136, v3, 15, s53
	v_ashrrev_i32_e32 v137, 31, v136
	v_lshlrev_b64 v[4:5], 6, v[136:137]
	v_lshl_add_u64 v[134:135], s[26:27], 0, v[4:5]
	s_mov_b32 s100, 0x2000
	s_mov_b32 s101, 0
	v_mov_b64_e32 v[202:203], v[134:135]
	v_lshl_add_u64 v[204:205], v[134:135], 0, s[100:101]
	global_load_dwordx4 v[170:173], v[202:203], off offset:32
	global_load_dwordx4 v[174:177], v[202:203], off offset:48
	global_load_dwordx4 v[178:181], v[202:203], off
	global_load_dwordx4 v[182:185], v[202:203], off offset:16
	global_load_dwordx4 v[186:189], v[202:203], off offset:1056
	global_load_dwordx4 v[190:193], v[202:203], off offset:1072
	global_load_dwordx4 v[194:197], v[202:203], off offset:1024
	global_load_dwordx4 v[198:201], v[202:203], off offset:1040
	s_waitcnt vmcnt(4)
	v_pk_add_f32 v[138:139], v[170:171], v[174:175]
	v_pk_add_f32 v[140:141], v[172:173], v[176:177]
	v_pk_add_f32 v[146:147], v[178:179], v[182:183]
	v_pk_add_f32 v[4:5], v[180:181], v[184:185]
	global_load_dwordx4 v[170:173], v[202:203], off offset:2080
	global_load_dwordx4 v[174:177], v[202:203], off offset:2096
	global_load_dwordx4 v[178:181], v[202:203], off offset:2048
	global_load_dwordx4 v[182:185], v[202:203], off offset:2064
	v_mov_b32_e32 v142, v138
	v_mov_b32_e32 v143, v146
	v_mov_b32_e32 v146, v139
	v_pk_add_f32 v[138:139], v[142:143], v[146:147]
	v_mov_b32_e32 v142, v140
	v_mov_b32_e32 v143, v4
	v_mov_b32_e32 v4, v141
	v_pk_add_f32 v[4:5], v[142:143], v[4:5]
	s_nop 0
	v_pk_add_f32 v[138:139], v[138:139], v[4:5]
	v_mov_b64_e32 v[4:5], s[8:9]
	v_pk_fma_f32 v[138:139], v[138:139], s[46:47], v[4:5] op_sel_hi:[1,0,0]
	s_nop 0
	v_div_scale_f32 v3, s[8:9], v139, v139, v138
	v_rcp_f32_e32 v137, v3
	s_nop 0
	v_fma_f32 v140, -v3, v137, 1.0
	v_fmac_f32_e32 v137, v140, v137
	v_div_scale_f32 v140, vcc, v138, v139, v138
	v_mul_f32_e32 v141, v140, v137
	v_fma_f32 v142, -v3, v141, v140
	v_fmac_f32_e32 v141, v142, v137
	v_fma_f32 v3, -v3, v141, v140
	v_div_fmas_f32 v3, v3, v137, v141
	v_div_fixup_f32 v3, v3, v139, v138
	v_cmp_gt_f32_e32 vcc, s50, v3
	v_mul_f32_e32 v137, 0x4f800000, v3
	s_nop 0
	v_cndmask_b32_e32 v3, v3, v137, vcc
	v_sqrt_f32_e32 v137, v3
	s_nop 0
	v_add_u32_e32 v138, -1, v137
	v_fma_f32 v139, -v138, v137, v3
	v_cmp_ge_f32_e64 s[8:9], 0, v139
	v_add_u32_e32 v139, 1, v137
	s_nop 0
	v_cndmask_b32_e64 v138, v137, v138, s[8:9]
	v_fma_f32 v137, -v139, v137, v3
	v_cmp_lt_f32_e64 s[8:9], 0, v137
	s_nop 1
	v_cndmask_b32_e64 v137, v138, v139, s[8:9]
	v_mul_f32_e32 v138, 0x37800000, v137
	v_cndmask_b32_e32 v137, v137, v138, vcc
	v_cmp_class_f32_e32 vcc, v3, v162
	s_nop 1
	v_cndmask_b32_e32 v138, v137, v3, vcc
	v_pk_mul_f32 v[132:133], v[132:133], v[138:139] op_sel_hi:[1,0]
	v_pk_mul_f32 v[130:131], v[130:131], v[138:139] op_sel_hi:[1,0]
	v_pk_mul_f32 v[128:129], v[128:129], v[138:139] op_sel_hi:[1,0]
	v_pk_mul_f32 v[126:127], v[126:127], v[138:139] op_sel_hi:[1,0]
	v_pk_mul_f32 v[124:125], v[124:125], v[138:139] op_sel_hi:[1,0]
	v_pk_mul_f32 v[122:123], v[122:123], v[138:139] op_sel_hi:[1,0]
	v_pk_mul_f32 v[120:121], v[120:121], v[138:139] op_sel_hi:[1,0]
	v_pk_mul_f32 v[118:119], v[118:119], v[138:139] op_sel_hi:[1,0]
	v_or_b32_e32 v138, 16, v136
	v_ashrrev_i32_e32 v139, 31, v138
	v_lshlrev_b64 v[138:139], 6, v[138:139]
	v_lshl_add_u64 v[166:167], s[26:27], 0, v[138:139]
	s_nop 0
	s_waitcnt vmcnt(6)
	v_pk_add_f32 v[138:139], v[186:187], v[190:191]
	v_pk_add_f32 v[140:141], v[188:189], v[192:193]
	s_waitcnt vmcnt(4)
	v_pk_add_f32 v[146:147], v[194:195], v[198:199]
	v_pk_add_f32 v[148:149], v[196:197], v[200:201]
	global_load_dwordx4 v[186:189], v[202:203], off offset:3104
	global_load_dwordx4 v[190:193], v[202:203], off offset:3120
	global_load_dwordx4 v[194:197], v[202:203], off offset:3072
	global_load_dwordx4 v[198:201], v[202:203], off offset:3088
	v_mov_b32_e32 v142, v138
	v_mov_b32_e32 v143, v146
	v_mov_b32_e32 v146, v139
	v_pk_add_f32 v[138:139], v[142:143], v[146:147]
	v_mov_b32_e32 v142, v140
	v_mov_b32_e32 v143, v148
	v_mov_b32_e32 v148, v141
	v_pk_add_f32 v[140:141], v[142:143], v[148:149]
	s_nop 0
	v_pk_add_f32 v[138:139], v[138:139], v[140:141]
	s_nop 0
	v_pk_fma_f32 v[138:139], v[138:139], s[46:47], v[4:5] op_sel_hi:[1,0,0]
	s_nop 0
	v_div_scale_f32 v3, s[8:9], v139, v139, v138
	v_rcp_f32_e32 v137, v3
	s_nop 0
	v_fma_f32 v140, -v3, v137, 1.0
	v_fmac_f32_e32 v137, v140, v137
	v_div_scale_f32 v140, vcc, v138, v139, v138
	v_mul_f32_e32 v141, v140, v137
	v_fma_f32 v142, -v3, v141, v140
	v_fmac_f32_e32 v141, v142, v137
	v_fma_f32 v3, -v3, v141, v140
	v_div_fmas_f32 v3, v3, v137, v141
	v_div_fixup_f32 v3, v3, v139, v138
	v_cmp_gt_f32_e32 vcc, s50, v3
	v_mul_f32_e32 v137, 0x4f800000, v3
	s_nop 0
	v_cndmask_b32_e32 v3, v3, v137, vcc
	v_sqrt_f32_e32 v137, v3
	s_nop 0
	v_add_u32_e32 v138, -1, v137
	v_fma_f32 v139, -v138, v137, v3
	v_cmp_ge_f32_e64 s[8:9], 0, v139
	v_add_u32_e32 v139, 1, v137
	s_nop 0
	v_cndmask_b32_e64 v138, v137, v138, s[8:9]
	v_fma_f32 v137, -v139, v137, v3
	v_cmp_lt_f32_e64 s[8:9], 0, v137
	s_nop 1
	v_cndmask_b32_e64 v137, v138, v139, s[8:9]
	v_mul_f32_e32 v138, 0x37800000, v137
	v_cndmask_b32_e32 v137, v137, v138, vcc
	v_cmp_class_f32_e32 vcc, v3, v162
	s_nop 1
	v_cndmask_b32_e32 v138, v137, v3, vcc
	v_pk_mul_f32 v[116:117], v[116:117], v[138:139] op_sel_hi:[1,0]
	v_pk_mul_f32 v[114:115], v[114:115], v[138:139] op_sel_hi:[1,0]
	v_pk_mul_f32 v[112:113], v[112:113], v[138:139] op_sel_hi:[1,0]
	v_pk_mul_f32 v[110:111], v[110:111], v[138:139] op_sel_hi:[1,0]
	v_pk_mul_f32 v[108:109], v[108:109], v[138:139] op_sel_hi:[1,0]
	v_pk_mul_f32 v[106:107], v[106:107], v[138:139] op_sel_hi:[1,0]
	v_pk_mul_f32 v[104:105], v[104:105], v[138:139] op_sel_hi:[1,0]
	v_pk_mul_f32 v[102:103], v[102:103], v[138:139] op_sel_hi:[1,0]
	v_or_b32_e32 v138, 32, v136
	v_ashrrev_i32_e32 v139, 31, v138
	v_lshlrev_b64 v[138:139], 6, v[138:139]
	v_lshl_add_u64 v[166:167], s[26:27], 0, v[138:139]
	s_nop 0
	v_or_b32_e32 v136, 48, v136
	s_waitcnt vmcnt(6)
	v_pk_add_f32 v[138:139], v[170:171], v[174:175]
	v_pk_add_f32 v[140:141], v[172:173], v[176:177]
	s_waitcnt vmcnt(4)
	v_pk_add_f32 v[146:147], v[178:179], v[182:183]
	v_pk_add_f32 v[148:149], v[180:181], v[184:185]
	global_load_dwordx4 v[170:173], v[204:205], off
	global_load_dwordx4 v[174:177], v[204:205], off offset:32
	global_load_dwordx4 v[178:181], v[204:205], off offset:48
	global_load_dwordx4 v[182:185], v[204:205], off offset:16
	v_mov_b32_e32 v142, v138
	v_mov_b32_e32 v143, v146
	v_mov_b32_e32 v146, v139
	v_pk_add_f32 v[138:139], v[142:143], v[146:147]
	v_mov_b32_e32 v142, v140
	v_mov_b32_e32 v143, v148
	v_mov_b32_e32 v148, v141
	v_pk_add_f32 v[140:141], v[142:143], v[148:149]
	s_nop 0
	v_pk_add_f32 v[138:139], v[138:139], v[140:141]
	s_nop 0
	v_pk_fma_f32 v[138:139], v[138:139], s[46:47], v[4:5] op_sel_hi:[1,0,0]
	s_nop 0
	v_div_scale_f32 v3, s[8:9], v139, v139, v138
	v_rcp_f32_e32 v137, v3
	s_nop 0
	v_fma_f32 v140, -v3, v137, 1.0
	v_fmac_f32_e32 v137, v140, v137
	v_div_scale_f32 v140, vcc, v138, v139, v138
	v_mul_f32_e32 v141, v140, v137
	v_fma_f32 v142, -v3, v141, v140
	v_fmac_f32_e32 v141, v142, v137
	v_fma_f32 v3, -v3, v141, v140
	v_div_fmas_f32 v3, v3, v137, v141
	v_div_fixup_f32 v3, v3, v139, v138
	v_cmp_gt_f32_e32 vcc, s50, v3
	v_mul_f32_e32 v137, 0x4f800000, v3
	s_nop 0
	v_cndmask_b32_e32 v3, v3, v137, vcc
	v_sqrt_f32_e32 v137, v3
	s_nop 0
	v_add_u32_e32 v138, -1, v137
	v_fma_f32 v139, -v138, v137, v3
	v_cmp_ge_f32_e64 s[8:9], 0, v139
	v_add_u32_e32 v139, 1, v137
	s_nop 0
	v_cndmask_b32_e64 v138, v137, v138, s[8:9]
	v_fma_f32 v137, -v139, v137, v3
	v_cmp_lt_f32_e64 s[8:9], 0, v137
	s_nop 1
	v_cndmask_b32_e64 v137, v138, v139, s[8:9]
	v_mul_f32_e32 v138, 0x37800000, v137
	v_cndmask_b32_e32 v137, v137, v138, vcc
	v_cmp_class_f32_e32 vcc, v3, v162
	s_nop 1
	v_cndmask_b32_e32 v138, v137, v3, vcc
	v_ashrrev_i32_e32 v137, 31, v136
	v_lshlrev_b64 v[136:137], 6, v[136:137]
	v_lshl_add_u64 v[148:149], s[26:27], 0, v[136:137]
	v_pk_mul_f32 v[100:101], v[100:101], v[138:139] op_sel_hi:[1,0]
	v_pk_mul_f32 v[98:99], v[98:99], v[138:139] op_sel_hi:[1,0]
	v_pk_mul_f32 v[96:97], v[96:97], v[138:139] op_sel_hi:[1,0]
	v_pk_mul_f32 v[94:95], v[94:95], v[138:139] op_sel_hi:[1,0]
	v_pk_mul_f32 v[92:93], v[92:93], v[138:139] op_sel_hi:[1,0]
	v_pk_mul_f32 v[90:91], v[90:91], v[138:139] op_sel_hi:[1,0]
	v_pk_mul_f32 v[88:89], v[88:89], v[138:139] op_sel_hi:[1,0]
	v_pk_mul_f32 v[86:87], v[86:87], v[138:139] op_sel_hi:[1,0]
	s_waitcnt vmcnt(6)
	v_pk_add_f32 v[136:137], v[186:187], v[190:191]
	v_pk_add_f32 v[138:139], v[188:189], v[192:193]
	s_waitcnt vmcnt(4)
	v_pk_add_f32 v[144:145], v[194:195], v[198:199]
	v_pk_add_f32 v[146:147], v[196:197], v[200:201]
	global_load_dwordx4 v[186:189], v[204:205], off offset:1024
	global_load_dwordx4 v[190:193], v[204:205], off offset:1056
	global_load_dwordx4 v[194:197], v[204:205], off offset:1072
	global_load_dwordx4 v[198:201], v[204:205], off offset:1040
	v_mov_b32_e32 v140, v136
	v_mov_b32_e32 v141, v144
	v_mov_b32_e32 v144, v137
	v_pk_add_f32 v[136:137], v[140:141], v[144:145]
	v_mov_b32_e32 v140, v138
	v_mov_b32_e32 v141, v146
	v_mov_b32_e32 v146, v139
	v_pk_add_f32 v[138:139], v[140:141], v[146:147]
	s_nop 0
	v_pk_add_f32 v[136:137], v[136:137], v[138:139]
	s_nop 0
	v_pk_fma_f32 v[136:137], v[136:137], s[46:47], v[4:5] op_sel_hi:[1,0,0]
	s_nop 0
	v_div_scale_f32 v3, s[8:9], v137, v137, v136
	v_rcp_f32_e32 v138, v3
	s_nop 0
	v_fma_f32 v139, -v3, v138, 1.0
	v_fmac_f32_e32 v138, v139, v138
	v_div_scale_f32 v139, vcc, v136, v137, v136
	v_mul_f32_e32 v140, v139, v138
	v_fma_f32 v141, -v3, v140, v139
	v_fmac_f32_e32 v140, v141, v138
	v_fma_f32 v3, -v3, v140, v139
	v_div_fmas_f32 v3, v3, v138, v140
	v_div_fixup_f32 v3, v3, v137, v136
	v_cmp_gt_f32_e32 vcc, s50, v3
	v_mul_f32_e32 v136, 0x4f800000, v3
	s_nop 0
	v_cndmask_b32_e32 v3, v3, v136, vcc
	v_sqrt_f32_e32 v136, v3
	s_nop 0
	v_add_u32_e32 v137, -1, v136
	v_fma_f32 v138, -v137, v136, v3
	v_cmp_ge_f32_e64 s[8:9], 0, v138
	v_add_u32_e32 v138, 1, v136
	s_nop 0
	v_cndmask_b32_e64 v137, v136, v137, s[8:9]
	v_fma_f32 v136, -v138, v136, v3
	v_cmp_lt_f32_e64 s[8:9], 0, v136
	s_nop 1
	v_cndmask_b32_e64 v136, v137, v138, s[8:9]
	v_mul_f32_e32 v137, 0x37800000, v136
	v_cndmask_b32_e32 v136, v136, v137, vcc
	v_cmp_class_f32_e32 vcc, v3, v162
	s_mov_b64 s[8:9], 0x2000
	v_lshl_add_u64 v[166:167], v[134:135], 0, s[8:9]
	v_cndmask_b32_e32 v136, v136, v3, vcc
	s_movk_i32 s8, 0x2000
	v_pk_mul_f32 v[84:85], v[84:85], v[136:137] op_sel_hi:[1,0]
	v_pk_mul_f32 v[82:83], v[82:83], v[136:137] op_sel_hi:[1,0]
	v_pk_mul_f32 v[80:81], v[80:81], v[136:137] op_sel_hi:[1,0]
	v_pk_mul_f32 v[78:79], v[78:79], v[136:137] op_sel_hi:[1,0]
	v_pk_mul_f32 v[76:77], v[76:77], v[136:137] op_sel_hi:[1,0]
	v_pk_mul_f32 v[74:75], v[74:75], v[136:137] op_sel_hi:[1,0]
	v_pk_mul_f32 v[72:73], v[72:73], v[136:137] op_sel_hi:[1,0]
	v_pk_mul_f32 v[70:71], v[70:71], v[136:137] op_sel_hi:[1,0]
	v_add_co_u32_e32 v136, vcc, s8, v134
	s_nop 1
	v_addc_co_u32_e32 v137, vcc, 0, v135, vcc
	s_nop 0
	s_waitcnt vmcnt(5)
	v_pk_add_f32 v[144:145], v[176:177], v[180:181]
	s_waitcnt vmcnt(4)
	v_pk_add_f32 v[140:141], v[172:173], v[184:185]
	v_pk_add_f32 v[138:139], v[170:171], v[182:183]
	v_pk_add_f32 v[142:143], v[174:175], v[178:179]
	global_load_dwordx4 v[170:173], v[204:205], off offset:2048
	global_load_dwordx4 v[174:177], v[204:205], off offset:2080
	global_load_dwordx4 v[178:181], v[204:205], off offset:2096
	global_load_dwordx4 v[182:185], v[204:205], off offset:2064
	v_mov_b32_e32 v147, v138
	v_mov_b32_e32 v146, v142
	v_mov_b32_e32 v138, v143
	v_mov_b32_e32 v142, v144
	v_mov_b32_e32 v143, v140
	v_mov_b32_e32 v140, v145
	v_pk_add_f32 v[138:139], v[146:147], v[138:139]
	v_pk_add_f32 v[140:141], v[142:143], v[140:141]
	s_nop 0
	v_pk_add_f32 v[138:139], v[138:139], v[140:141]
	s_nop 0
	v_pk_fma_f32 v[138:139], v[138:139], s[46:47], v[4:5] op_sel_hi:[1,0,0]
	s_nop 0
	v_div_scale_f32 v3, s[8:9], v139, v139, v138
	v_rcp_f32_e32 v140, v3
	s_nop 0
	v_fma_f32 v141, -v3, v140, 1.0
	v_fmac_f32_e32 v140, v141, v140
	v_div_scale_f32 v141, vcc, v138, v139, v138
	v_mul_f32_e32 v142, v141, v140
	v_fma_f32 v143, -v3, v142, v141
	v_fmac_f32_e32 v142, v143, v140
	v_fma_f32 v3, -v3, v142, v141
	v_div_fmas_f32 v3, v3, v140, v142
	v_div_fixup_f32 v3, v3, v139, v138
	v_cmp_gt_f32_e32 vcc, s50, v3
	v_mul_f32_e32 v138, 0x4f800000, v3
	s_nop 0
	v_cndmask_b32_e32 v3, v3, v138, vcc
	v_sqrt_f32_e32 v138, v3
	s_nop 0
	v_add_u32_e32 v139, -1, v138
	v_fma_f32 v140, -v139, v138, v3
	v_cmp_ge_f32_e64 s[8:9], 0, v140
	v_add_u32_e32 v140, 1, v138
	s_nop 0
	v_cndmask_b32_e64 v139, v138, v139, s[8:9]
	v_fma_f32 v138, -v140, v138, v3
	v_cmp_lt_f32_e64 s[8:9], 0, v138
	s_nop 1
	v_cndmask_b32_e64 v138, v139, v140, s[8:9]
	v_mul_f32_e32 v139, 0x37800000, v138
	v_cndmask_b32_e32 v138, v138, v139, vcc
	v_cmp_class_f32_e32 vcc, v3, v162
	s_mov_b64 s[8:9], 0x2400
	v_lshl_add_u64 v[166:167], v[134:135], 0, s[8:9]
	v_cndmask_b32_e32 v138, v138, v3, vcc
	v_pk_mul_f32 v[68:69], v[68:69], v[138:139] op_sel_hi:[1,0]
	v_pk_mul_f32 v[66:67], v[66:67], v[138:139] op_sel_hi:[1,0]
	v_pk_mul_f32 v[64:65], v[64:65], v[138:139] op_sel_hi:[1,0]
	v_pk_mul_f32 v[62:63], v[62:63], v[138:139] op_sel_hi:[1,0]
	v_pk_mul_f32 v[60:61], v[60:61], v[138:139] op_sel_hi:[1,0]
	v_pk_mul_f32 v[58:59], v[58:59], v[138:139] op_sel_hi:[1,0]
	v_pk_mul_f32 v[56:57], v[56:57], v[138:139] op_sel_hi:[1,0]
	v_pk_mul_f32 v[54:55], v[54:55], v[138:139] op_sel_hi:[1,0]
	s_nop 0
	s_waitcnt vmcnt(5)
	v_pk_add_f32 v[144:145], v[192:193], v[196:197]
	s_waitcnt vmcnt(4)
	v_pk_add_f32 v[140:141], v[188:189], v[200:201]
	v_pk_add_f32 v[138:139], v[186:187], v[198:199]
	v_pk_add_f32 v[142:143], v[190:191], v[194:195]
	global_load_dwordx4 v[186:189], v[204:205], off offset:3072
	global_load_dwordx4 v[190:193], v[204:205], off offset:3104
	global_load_dwordx4 v[194:197], v[204:205], off offset:3120
	global_load_dwordx4 v[198:201], v[204:205], off offset:3088
	v_mov_b32_e32 v147, v138
	v_mov_b32_e32 v146, v142
	v_mov_b32_e32 v138, v143
	v_mov_b32_e32 v142, v144
	v_mov_b32_e32 v143, v140
	v_mov_b32_e32 v140, v145
	v_pk_add_f32 v[138:139], v[146:147], v[138:139]
	v_pk_add_f32 v[140:141], v[142:143], v[140:141]
	s_nop 0
	v_pk_add_f32 v[138:139], v[138:139], v[140:141]
	s_nop 0
	v_pk_fma_f32 v[138:139], v[138:139], s[46:47], v[4:5] op_sel_hi:[1,0,0]
	s_nop 0
	v_div_scale_f32 v3, s[8:9], v139, v139, v138
	v_rcp_f32_e32 v140, v3
	s_nop 0
	v_fma_f32 v141, -v3, v140, 1.0
	v_fmac_f32_e32 v140, v141, v140
	v_div_scale_f32 v141, vcc, v138, v139, v138
	v_mul_f32_e32 v142, v141, v140
	v_fma_f32 v143, -v3, v142, v141
	v_fmac_f32_e32 v142, v143, v140
	v_fma_f32 v3, -v3, v142, v141
	v_div_fmas_f32 v3, v3, v140, v142
	v_div_fixup_f32 v3, v3, v139, v138
	v_cmp_gt_f32_e32 vcc, s50, v3
	v_mul_f32_e32 v138, 0x4f800000, v3
	s_nop 0
	v_cndmask_b32_e32 v3, v3, v138, vcc
	v_sqrt_f32_e32 v138, v3
	s_nop 0
	v_add_u32_e32 v139, -1, v138
	v_fma_f32 v140, -v139, v138, v3
	v_cmp_ge_f32_e64 s[8:9], 0, v140
	v_add_u32_e32 v140, 1, v138
	s_nop 0
	v_cndmask_b32_e64 v139, v138, v139, s[8:9]
	v_fma_f32 v138, -v140, v138, v3
	v_cmp_lt_f32_e64 s[8:9], 0, v138
	s_nop 1
	v_cndmask_b32_e64 v138, v139, v140, s[8:9]
	v_mul_f32_e32 v139, 0x37800000, v138
	v_cndmask_b32_e32 v138, v138, v139, vcc
	v_cmp_class_f32_e32 vcc, v3, v162
	s_mov_b64 s[8:9], 0x2800
	v_lshl_add_u64 v[166:167], v[134:135], 0, s[8:9]
	v_cndmask_b32_e32 v138, v138, v3, vcc
	v_pk_mul_f32 v[52:53], v[52:53], v[138:139] op_sel_hi:[1,0]
	v_pk_mul_f32 v[50:51], v[50:51], v[138:139] op_sel_hi:[1,0]
	v_pk_mul_f32 v[48:49], v[48:49], v[138:139] op_sel_hi:[1,0]
	v_pk_mul_f32 v[46:47], v[46:47], v[138:139] op_sel_hi:[1,0]
	v_pk_mul_f32 v[44:45], v[44:45], v[138:139] op_sel_hi:[1,0]
	v_pk_mul_f32 v[42:43], v[42:43], v[138:139] op_sel_hi:[1,0]
	v_pk_mul_f32 v[40:41], v[40:41], v[138:139] op_sel_hi:[1,0]
	v_pk_mul_f32 v[38:39], v[38:39], v[138:139] op_sel_hi:[1,0]
	s_nop 0
	s_waitcnt vmcnt(5)
	v_pk_add_f32 v[144:145], v[176:177], v[180:181]
	s_waitcnt vmcnt(4)
	v_pk_add_f32 v[140:141], v[172:173], v[184:185]
	v_pk_add_f32 v[138:139], v[170:171], v[182:183]
	v_pk_add_f32 v[142:143], v[174:175], v[178:179]
	v_mov_b32_e32 v147, v138
	v_mov_b32_e32 v146, v142
	v_mov_b32_e32 v138, v143
	v_mov_b32_e32 v142, v144
	v_mov_b32_e32 v143, v140
	v_mov_b32_e32 v140, v145
	v_pk_add_f32 v[138:139], v[146:147], v[138:139]
	v_pk_add_f32 v[140:141], v[142:143], v[140:141]
	s_nop 0
	v_pk_add_f32 v[138:139], v[138:139], v[140:141]
	s_nop 0
	v_pk_fma_f32 v[138:139], v[138:139], s[46:47], v[4:5] op_sel_hi:[1,0,0]
	s_nop 0
	v_div_scale_f32 v3, s[8:9], v139, v139, v138
	v_rcp_f32_e32 v140, v3
	s_nop 0
	v_fma_f32 v141, -v3, v140, 1.0
	v_fmac_f32_e32 v140, v141, v140
	v_div_scale_f32 v141, vcc, v138, v139, v138
	v_mul_f32_e32 v142, v141, v140
	v_fma_f32 v143, -v3, v142, v141
	v_fmac_f32_e32 v142, v143, v140
	v_fma_f32 v3, -v3, v142, v141
	v_div_fmas_f32 v3, v3, v140, v142
	v_div_fixup_f32 v3, v3, v139, v138
	v_cmp_gt_f32_e32 vcc, s50, v3
	v_mul_f32_e32 v138, 0x4f800000, v3
	s_nop 0
	v_cndmask_b32_e32 v3, v3, v138, vcc
	v_sqrt_f32_e32 v138, v3
	s_nop 0
	v_add_u32_e32 v139, -1, v138
	v_fma_f32 v140, -v139, v138, v3
	v_cmp_ge_f32_e64 s[8:9], 0, v140
	v_add_u32_e32 v140, 1, v138
	s_nop 0
	v_cndmask_b32_e64 v139, v138, v139, s[8:9]
	v_fma_f32 v138, -v140, v138, v3
	v_cmp_lt_f32_e64 s[8:9], 0, v138
	s_nop 1
	v_cndmask_b32_e64 v138, v139, v140, s[8:9]
	v_mul_f32_e32 v139, 0x37800000, v138
	v_cndmask_b32_e32 v138, v138, v139, vcc
	v_cmp_class_f32_e32 vcc, v3, v162
	s_mov_b64 s[8:9], 0x2c00
	v_lshl_add_u64 v[146:147], v[134:135], 0, s[8:9]
	v_cndmask_b32_e32 v138, v138, v3, vcc
	v_pk_mul_f32 v[36:37], v[36:37], v[138:139] op_sel_hi:[1,0]
	v_pk_mul_f32 v[34:35], v[34:35], v[138:139] op_sel_hi:[1,0]
	v_pk_mul_f32 v[32:33], v[32:33], v[138:139] op_sel_hi:[1,0]
	v_pk_mul_f32 v[30:31], v[30:31], v[138:139] op_sel_hi:[1,0]
	v_pk_mul_f32 v[28:29], v[28:29], v[138:139] op_sel_hi:[1,0]
	v_pk_mul_f32 v[26:27], v[26:27], v[138:139] op_sel_hi:[1,0]
	v_pk_mul_f32 v[24:25], v[24:25], v[138:139] op_sel_hi:[1,0]
	v_pk_mul_f32 v[22:23], v[22:23], v[138:139] op_sel_hi:[1,0]
	s_nop 0
	s_nop 0
	s_waitcnt vmcnt(1)
	v_pk_add_f32 v[134:135], v[190:191], v[194:195]
	s_waitcnt vmcnt(0)
	v_pk_add_f32 v[142:143], v[186:187], v[198:199]
	v_pk_add_f32 v[144:145], v[188:189], v[200:201]
	v_pk_add_f32 v[136:137], v[192:193], v[196:197]
	v_mov_b32_e32 v138, v134
	v_mov_b32_e32 v139, v142
	v_mov_b32_e32 v142, v135
	v_pk_add_f32 v[134:135], v[138:139], v[142:143]
	v_mov_b32_e32 v138, v136
	v_mov_b32_e32 v139, v144
	v_mov_b32_e32 v144, v137
	v_pk_add_f32 v[136:137], v[138:139], v[144:145]
	s_nop 0
	v_pk_add_f32 v[134:135], v[134:135], v[136:137]
	s_nop 0
	v_pk_fma_f32 v[4:5], v[134:135], s[46:47], v[4:5] op_sel_hi:[1,0,0]
	s_nop 0
	v_div_scale_f32 v3, s[8:9], v5, v5, v4
	v_rcp_f32_e32 v134, v3
	s_nop 0
	v_fma_f32 v135, -v3, v134, 1.0
	v_fmac_f32_e32 v134, v135, v134
	v_div_scale_f32 v135, vcc, v4, v5, v4
	v_mul_f32_e32 v136, v135, v134
	v_fma_f32 v137, -v3, v136, v135
	v_fmac_f32_e32 v136, v137, v134
	v_fma_f32 v3, -v3, v136, v135
	v_div_fmas_f32 v3, v3, v134, v136
	v_div_fixup_f32 v3, v3, v5, v4
	v_cmp_gt_f32_e32 vcc, s50, v3
	v_mul_f32_e32 v4, 0x4f800000, v3
	s_nop 0
	v_cndmask_b32_e32 v3, v3, v4, vcc
	v_sqrt_f32_e32 v4, v3
	s_nop 0
	v_add_u32_e32 v5, -1, v4
	v_fma_f32 v134, -v5, v4, v3
	v_cmp_ge_f32_e64 s[8:9], 0, v134
	v_add_u32_e32 v134, 1, v4
	s_nop 0
	v_cndmask_b32_e64 v5, v4, v5, s[8:9]
	v_fma_f32 v4, -v134, v4, v3
	v_cmp_lt_f32_e64 s[8:9], 0, v4
	s_nop 1
	v_cndmask_b32_e64 v4, v5, v134, s[8:9]
	v_mul_f32_e32 v5, 0x37800000, v4
	v_cndmask_b32_e32 v4, v4, v5, vcc
	v_cmp_class_f32_e32 vcc, v3, v162
	s_nop 1
	v_cndmask_b32_e32 v4, v4, v3, vcc
	v_pk_mul_f32 v[20:21], v[20:21], v[4:5] op_sel_hi:[1,0]
	v_pk_mul_f32 v[18:19], v[18:19], v[4:5] op_sel_hi:[1,0]
	v_pk_mul_f32 v[16:17], v[16:17], v[4:5] op_sel_hi:[1,0]
	v_pk_mul_f32 v[14:15], v[14:15], v[4:5] op_sel_hi:[1,0]
	v_pk_mul_f32 v[12:13], v[12:13], v[4:5] op_sel_hi:[1,0]
	v_pk_mul_f32 v[10:11], v[10:11], v[4:5] op_sel_hi:[1,0]
	v_pk_mul_f32 v[8:9], v[8:9], v[4:5] op_sel_hi:[1,0]
	v_pk_mul_f32 v[6:7], v[6:7], v[4:5] op_sel_hi:[1,0]
	s_branch .LBB0_857

.LBB0_1881:
	s_cmpk_lg_i32 s64, 0x800
	s_cbranch_scc1 .LBB0_1880
	v_mov_b32_e32 v3, v0
	s_mov_b32 s8, 0x358637bd
	v_and_or_b32 v136, v3, 15, s4
	v_ashrrev_i32_e32 v137, 31, v136
	v_lshlrev_b64 v[4:5], 6, v[136:137]
	v_lshl_add_u64 v[134:135], s[22:23], 0, v[4:5]
	s_mov_b32 s100, 0x2000
	s_mov_b32 s101, 0
	v_mov_b64_e32 v[206:207], v[134:135]
	v_lshl_add_u64 v[208:209], v[134:135], 0, s[100:101]
	global_load_dwordx4 v[156:159], v[206:207], off offset:32
	global_load_dwordx4 v[160:163], v[206:207], off offset:48
	global_load_dwordx4 v[182:185], v[206:207], off
	global_load_dwordx4 v[186:189], v[206:207], off offset:16
	global_load_dwordx4 v[190:193], v[206:207], off offset:1056
	global_load_dwordx4 v[194:197], v[206:207], off offset:1072
	global_load_dwordx4 v[198:201], v[206:207], off offset:1024
	global_load_dwordx4 v[202:205], v[206:207], off offset:1040
	s_waitcnt vmcnt(4)
	v_pk_add_f32 v[138:139], v[156:157], v[160:161]
	v_pk_add_f32 v[140:141], v[158:159], v[162:163]
	v_pk_add_f32 v[146:147], v[182:183], v[186:187]
	v_pk_add_f32 v[4:5], v[184:185], v[188:189]
	global_load_dwordx4 v[156:159], v[206:207], off offset:2080
	global_load_dwordx4 v[160:163], v[206:207], off offset:2096
	global_load_dwordx4 v[182:185], v[206:207], off offset:2048
	global_load_dwordx4 v[186:189], v[206:207], off offset:2064
	v_mov_b32_e32 v142, v138
	v_mov_b32_e32 v143, v146
	v_mov_b32_e32 v146, v139
	v_pk_add_f32 v[138:139], v[142:143], v[146:147]
	v_mov_b32_e32 v142, v140
	v_mov_b32_e32 v143, v4
	v_mov_b32_e32 v4, v141
	v_pk_add_f32 v[4:5], v[142:143], v[4:5]
	s_nop 0
	v_pk_add_f32 v[138:139], v[138:139], v[4:5]
	v_mov_b64_e32 v[4:5], s[8:9]
	v_pk_fma_f32 v[138:139], v[138:139], s[44:45], v[4:5] op_sel_hi:[1,0,0]
	s_nop 0
	v_div_scale_f32 v3, s[8:9], v139, v139, v138
	v_rcp_f32_e32 v137, v3
	s_nop 0
	v_fma_f32 v140, -v3, v137, 1.0
	v_fmac_f32_e32 v137, v140, v137
	v_div_scale_f32 v140, vcc, v138, v139, v138
	v_mul_f32_e32 v141, v140, v137
	v_fma_f32 v142, -v3, v141, v140
	v_fmac_f32_e32 v141, v142, v137
	v_fma_f32 v3, -v3, v141, v140
	v_div_fmas_f32 v3, v3, v137, v141
	v_div_fixup_f32 v3, v3, v139, v138
	v_cmp_gt_f32_e32 vcc, s76, v3
	v_mul_f32_e32 v137, 0x4f800000, v3
	s_nop 0
	v_cndmask_b32_e32 v3, v3, v137, vcc
	v_sqrt_f32_e32 v137, v3
	s_nop 0
	v_add_u32_e32 v138, -1, v137
	v_fma_f32 v139, -v138, v137, v3
	v_cmp_ge_f32_e64 s[8:9], 0, v139
	v_add_u32_e32 v139, 1, v137
	s_nop 0
	v_cndmask_b32_e64 v138, v137, v138, s[8:9]
	v_fma_f32 v137, -v139, v137, v3
	v_cmp_lt_f32_e64 s[8:9], 0, v137
	s_nop 1
	v_cndmask_b32_e64 v137, v138, v139, s[8:9]
	v_mul_f32_e32 v138, 0x37800000, v137
	v_cndmask_b32_e32 v137, v137, v138, vcc
	v_cmp_class_f32_e32 vcc, v3, v178
	s_nop 1
	v_cndmask_b32_e32 v138, v137, v3, vcc
	v_pk_mul_f32 v[132:133], v[132:133], v[138:139] op_sel_hi:[1,0]
	v_pk_mul_f32 v[130:131], v[130:131], v[138:139] op_sel_hi:[1,0]
	v_pk_mul_f32 v[128:129], v[128:129], v[138:139] op_sel_hi:[1,0]
	v_pk_mul_f32 v[126:127], v[126:127], v[138:139] op_sel_hi:[1,0]
	v_pk_mul_f32 v[124:125], v[124:125], v[138:139] op_sel_hi:[1,0]
	v_pk_mul_f32 v[122:123], v[122:123], v[138:139] op_sel_hi:[1,0]
	v_pk_mul_f32 v[120:121], v[120:121], v[138:139] op_sel_hi:[1,0]
	v_pk_mul_f32 v[118:119], v[118:119], v[138:139] op_sel_hi:[1,0]
	v_or_b32_e32 v138, 16, v136
	v_ashrrev_i32_e32 v139, 31, v138
	v_lshlrev_b64 v[138:139], 6, v[138:139]
	v_lshl_add_u64 v[152:153], s[22:23], 0, v[138:139]
	s_nop 0
	s_waitcnt vmcnt(6)
	v_pk_add_f32 v[138:139], v[190:191], v[194:195]
	v_pk_add_f32 v[140:141], v[192:193], v[196:197]
	s_waitcnt vmcnt(4)
	v_pk_add_f32 v[146:147], v[198:199], v[202:203]
	v_pk_add_f32 v[148:149], v[200:201], v[204:205]
	global_load_dwordx4 v[190:193], v[206:207], off offset:3104
	global_load_dwordx4 v[194:197], v[206:207], off offset:3120
	global_load_dwordx4 v[198:201], v[206:207], off offset:3072
	global_load_dwordx4 v[202:205], v[206:207], off offset:3088
	v_mov_b32_e32 v142, v138
	v_mov_b32_e32 v143, v146
	v_mov_b32_e32 v146, v139
	v_pk_add_f32 v[138:139], v[142:143], v[146:147]
	v_mov_b32_e32 v142, v140
	v_mov_b32_e32 v143, v148
	v_mov_b32_e32 v148, v141
	v_pk_add_f32 v[140:141], v[142:143], v[148:149]
	s_nop 0
	v_pk_add_f32 v[138:139], v[138:139], v[140:141]
	s_nop 0
	v_pk_fma_f32 v[138:139], v[138:139], s[44:45], v[4:5] op_sel_hi:[1,0,0]
	s_nop 0
	v_div_scale_f32 v3, s[8:9], v139, v139, v138
	v_rcp_f32_e32 v137, v3
	s_nop 0
	v_fma_f32 v140, -v3, v137, 1.0
	v_fmac_f32_e32 v137, v140, v137
	v_div_scale_f32 v140, vcc, v138, v139, v138
	v_mul_f32_e32 v141, v140, v137
	v_fma_f32 v142, -v3, v141, v140
	v_fmac_f32_e32 v141, v142, v137
	v_fma_f32 v3, -v3, v141, v140
	v_div_fmas_f32 v3, v3, v137, v141
	v_div_fixup_f32 v3, v3, v139, v138
	v_cmp_gt_f32_e32 vcc, s76, v3
	v_mul_f32_e32 v137, 0x4f800000, v3
	s_nop 0
	v_cndmask_b32_e32 v3, v3, v137, vcc
	v_sqrt_f32_e32 v137, v3
	s_nop 0
	v_add_u32_e32 v138, -1, v137
	v_fma_f32 v139, -v138, v137, v3
	v_cmp_ge_f32_e64 s[8:9], 0, v139
	v_add_u32_e32 v139, 1, v137
	s_nop 0
	v_cndmask_b32_e64 v138, v137, v138, s[8:9]
	v_fma_f32 v137, -v139, v137, v3
	v_cmp_lt_f32_e64 s[8:9], 0, v137
	s_nop 1
	v_cndmask_b32_e64 v137, v138, v139, s[8:9]
	v_mul_f32_e32 v138, 0x37800000, v137
	v_cndmask_b32_e32 v137, v137, v138, vcc
	v_cmp_class_f32_e32 vcc, v3, v178
	s_nop 1
	v_cndmask_b32_e32 v138, v137, v3, vcc
	v_pk_mul_f32 v[116:117], v[116:117], v[138:139] op_sel_hi:[1,0]
	v_pk_mul_f32 v[114:115], v[114:115], v[138:139] op_sel_hi:[1,0]
	v_pk_mul_f32 v[112:113], v[112:113], v[138:139] op_sel_hi:[1,0]
	v_pk_mul_f32 v[110:111], v[110:111], v[138:139] op_sel_hi:[1,0]
	v_pk_mul_f32 v[108:109], v[108:109], v[138:139] op_sel_hi:[1,0]
	v_pk_mul_f32 v[106:107], v[106:107], v[138:139] op_sel_hi:[1,0]
	v_pk_mul_f32 v[104:105], v[104:105], v[138:139] op_sel_hi:[1,0]
	v_pk_mul_f32 v[102:103], v[102:103], v[138:139] op_sel_hi:[1,0]
	v_or_b32_e32 v138, 32, v136
	v_ashrrev_i32_e32 v139, 31, v138
	v_lshlrev_b64 v[138:139], 6, v[138:139]
	v_lshl_add_u64 v[152:153], s[22:23], 0, v[138:139]
	s_nop 0
	v_or_b32_e32 v136, 48, v136
	s_waitcnt vmcnt(6)
	v_pk_add_f32 v[138:139], v[156:157], v[160:161]
	v_pk_add_f32 v[140:141], v[158:159], v[162:163]
	s_waitcnt vmcnt(4)
	v_pk_add_f32 v[146:147], v[182:183], v[186:187]
	v_pk_add_f32 v[148:149], v[184:185], v[188:189]
	global_load_dwordx4 v[156:159], v[208:209], off
	global_load_dwordx4 v[160:163], v[208:209], off offset:32
	global_load_dwordx4 v[182:185], v[208:209], off offset:48
	global_load_dwordx4 v[186:189], v[208:209], off offset:16
	v_mov_b32_e32 v142, v138
	v_mov_b32_e32 v143, v146
	v_mov_b32_e32 v146, v139
	v_pk_add_f32 v[138:139], v[142:143], v[146:147]
	v_mov_b32_e32 v142, v140
	v_mov_b32_e32 v143, v148
	v_mov_b32_e32 v148, v141
	v_pk_add_f32 v[140:141], v[142:143], v[148:149]
	s_nop 0
	v_pk_add_f32 v[138:139], v[138:139], v[140:141]
	s_nop 0
	v_pk_fma_f32 v[138:139], v[138:139], s[44:45], v[4:5] op_sel_hi:[1,0,0]
	s_nop 0
	v_div_scale_f32 v3, s[8:9], v139, v139, v138
	v_rcp_f32_e32 v137, v3
	s_nop 0
	v_fma_f32 v140, -v3, v137, 1.0
	v_fmac_f32_e32 v137, v140, v137
	v_div_scale_f32 v140, vcc, v138, v139, v138
	v_mul_f32_e32 v141, v140, v137
	v_fma_f32 v142, -v3, v141, v140
	v_fmac_f32_e32 v141, v142, v137
	v_fma_f32 v3, -v3, v141, v140
	v_div_fmas_f32 v3, v3, v137, v141
	v_div_fixup_f32 v3, v3, v139, v138
	v_cmp_gt_f32_e32 vcc, s76, v3
	v_mul_f32_e32 v137, 0x4f800000, v3
	s_nop 0
	v_cndmask_b32_e32 v3, v3, v137, vcc
	v_sqrt_f32_e32 v137, v3
	s_nop 0
	v_add_u32_e32 v138, -1, v137
	v_fma_f32 v139, -v138, v137, v3
	v_cmp_ge_f32_e64 s[8:9], 0, v139
	v_add_u32_e32 v139, 1, v137
	s_nop 0
	v_cndmask_b32_e64 v138, v137, v138, s[8:9]
	v_fma_f32 v137, -v139, v137, v3
	v_cmp_lt_f32_e64 s[8:9], 0, v137
	s_nop 1
	v_cndmask_b32_e64 v137, v138, v139, s[8:9]
	v_mul_f32_e32 v138, 0x37800000, v137
	v_cndmask_b32_e32 v137, v137, v138, vcc
	v_cmp_class_f32_e32 vcc, v3, v178
	s_nop 1
	v_cndmask_b32_e32 v138, v137, v3, vcc
	v_ashrrev_i32_e32 v137, 31, v136
	v_lshlrev_b64 v[136:137], 6, v[136:137]
	v_lshl_add_u64 v[148:149], s[22:23], 0, v[136:137]
	v_pk_mul_f32 v[100:101], v[100:101], v[138:139] op_sel_hi:[1,0]
	v_pk_mul_f32 v[98:99], v[98:99], v[138:139] op_sel_hi:[1,0]
	v_pk_mul_f32 v[96:97], v[96:97], v[138:139] op_sel_hi:[1,0]
	v_pk_mul_f32 v[94:95], v[94:95], v[138:139] op_sel_hi:[1,0]
	v_pk_mul_f32 v[92:93], v[92:93], v[138:139] op_sel_hi:[1,0]
	v_pk_mul_f32 v[90:91], v[90:91], v[138:139] op_sel_hi:[1,0]
	v_pk_mul_f32 v[88:89], v[88:89], v[138:139] op_sel_hi:[1,0]
	v_pk_mul_f32 v[86:87], v[86:87], v[138:139] op_sel_hi:[1,0]
	s_waitcnt vmcnt(6)
	v_pk_add_f32 v[136:137], v[190:191], v[194:195]
	v_pk_add_f32 v[138:139], v[192:193], v[196:197]
	s_waitcnt vmcnt(4)
	v_pk_add_f32 v[144:145], v[198:199], v[202:203]
	v_pk_add_f32 v[146:147], v[200:201], v[204:205]
	global_load_dwordx4 v[190:193], v[208:209], off offset:1024
	global_load_dwordx4 v[194:197], v[208:209], off offset:1056
	global_load_dwordx4 v[198:201], v[208:209], off offset:1072
	global_load_dwordx4 v[202:205], v[208:209], off offset:1040
	v_mov_b32_e32 v140, v136
	v_mov_b32_e32 v141, v144
	v_mov_b32_e32 v144, v137
	v_pk_add_f32 v[136:137], v[140:141], v[144:145]
	v_mov_b32_e32 v140, v138
	v_mov_b32_e32 v141, v146
	v_mov_b32_e32 v146, v139
	v_pk_add_f32 v[138:139], v[140:141], v[146:147]
	s_nop 0
	v_pk_add_f32 v[136:137], v[136:137], v[138:139]
	s_nop 0
	v_pk_fma_f32 v[136:137], v[136:137], s[44:45], v[4:5] op_sel_hi:[1,0,0]
	s_nop 0
	v_div_scale_f32 v3, s[8:9], v137, v137, v136
	v_rcp_f32_e32 v138, v3
	s_nop 0
	v_fma_f32 v139, -v3, v138, 1.0
	v_fmac_f32_e32 v138, v139, v138
	v_div_scale_f32 v139, vcc, v136, v137, v136
	v_mul_f32_e32 v140, v139, v138
	v_fma_f32 v141, -v3, v140, v139
	v_fmac_f32_e32 v140, v141, v138
	v_fma_f32 v3, -v3, v140, v139
	v_div_fmas_f32 v3, v3, v138, v140
	v_div_fixup_f32 v3, v3, v137, v136
	v_cmp_gt_f32_e32 vcc, s76, v3
	v_mul_f32_e32 v136, 0x4f800000, v3
	s_nop 0
	v_cndmask_b32_e32 v3, v3, v136, vcc
	v_sqrt_f32_e32 v136, v3
	s_nop 0
	v_add_u32_e32 v137, -1, v136
	v_fma_f32 v138, -v137, v136, v3
	v_cmp_ge_f32_e64 s[8:9], 0, v138
	v_add_u32_e32 v138, 1, v136
	s_nop 0
	v_cndmask_b32_e64 v137, v136, v137, s[8:9]
	v_fma_f32 v136, -v138, v136, v3
	v_cmp_lt_f32_e64 s[8:9], 0, v136
	s_nop 1
	v_cndmask_b32_e64 v136, v137, v138, s[8:9]
	v_mul_f32_e32 v137, 0x37800000, v136
	v_cndmask_b32_e32 v136, v136, v137, vcc
	v_cmp_class_f32_e32 vcc, v3, v178
	s_mov_b64 s[8:9], 0x2000
	v_lshl_add_u64 v[152:153], v[134:135], 0, s[8:9]
	v_cndmask_b32_e32 v136, v136, v3, vcc
	s_movk_i32 s8, 0x2000
	v_pk_mul_f32 v[84:85], v[84:85], v[136:137] op_sel_hi:[1,0]
	v_pk_mul_f32 v[82:83], v[82:83], v[136:137] op_sel_hi:[1,0]
	v_pk_mul_f32 v[80:81], v[80:81], v[136:137] op_sel_hi:[1,0]
	v_pk_mul_f32 v[78:79], v[78:79], v[136:137] op_sel_hi:[1,0]
	v_pk_mul_f32 v[76:77], v[76:77], v[136:137] op_sel_hi:[1,0]
	v_pk_mul_f32 v[74:75], v[74:75], v[136:137] op_sel_hi:[1,0]
	v_pk_mul_f32 v[72:73], v[72:73], v[136:137] op_sel_hi:[1,0]
	v_pk_mul_f32 v[70:71], v[70:71], v[136:137] op_sel_hi:[1,0]
	v_add_co_u32_e32 v136, vcc, s8, v134
	s_nop 1
	v_addc_co_u32_e32 v137, vcc, 0, v135, vcc
	s_nop 0
	s_waitcnt vmcnt(5)
	v_pk_add_f32 v[144:145], v[162:163], v[184:185]
	s_waitcnt vmcnt(4)
	v_pk_add_f32 v[140:141], v[158:159], v[188:189]
	v_pk_add_f32 v[138:139], v[156:157], v[186:187]
	v_pk_add_f32 v[142:143], v[160:161], v[182:183]
	global_load_dwordx4 v[156:159], v[208:209], off offset:2048
	global_load_dwordx4 v[160:163], v[208:209], off offset:2080
	global_load_dwordx4 v[182:185], v[208:209], off offset:2096
	global_load_dwordx4 v[186:189], v[208:209], off offset:2064
	v_mov_b32_e32 v147, v138
	v_mov_b32_e32 v146, v142
	v_mov_b32_e32 v138, v143
	v_mov_b32_e32 v142, v144
	v_mov_b32_e32 v143, v140
	v_mov_b32_e32 v140, v145
	v_pk_add_f32 v[138:139], v[146:147], v[138:139]
	v_pk_add_f32 v[140:141], v[142:143], v[140:141]
	s_nop 0
	v_pk_add_f32 v[138:139], v[138:139], v[140:141]
	s_nop 0
	v_pk_fma_f32 v[138:139], v[138:139], s[44:45], v[4:5] op_sel_hi:[1,0,0]
	s_nop 0
	v_div_scale_f32 v3, s[8:9], v139, v139, v138
	v_rcp_f32_e32 v140, v3
	s_nop 0
	v_fma_f32 v141, -v3, v140, 1.0
	v_fmac_f32_e32 v140, v141, v140
	v_div_scale_f32 v141, vcc, v138, v139, v138
	v_mul_f32_e32 v142, v141, v140
	v_fma_f32 v143, -v3, v142, v141
	v_fmac_f32_e32 v142, v143, v140
	v_fma_f32 v3, -v3, v142, v141
	v_div_fmas_f32 v3, v3, v140, v142
	v_div_fixup_f32 v3, v3, v139, v138
	v_cmp_gt_f32_e32 vcc, s76, v3
	v_mul_f32_e32 v138, 0x4f800000, v3
	s_nop 0
	v_cndmask_b32_e32 v3, v3, v138, vcc
	v_sqrt_f32_e32 v138, v3
	s_nop 0
	v_add_u32_e32 v139, -1, v138
	v_fma_f32 v140, -v139, v138, v3
	v_cmp_ge_f32_e64 s[8:9], 0, v140
	v_add_u32_e32 v140, 1, v138
	s_nop 0
	v_cndmask_b32_e64 v139, v138, v139, s[8:9]
	v_fma_f32 v138, -v140, v138, v3
	v_cmp_lt_f32_e64 s[8:9], 0, v138
	s_nop 1
	v_cndmask_b32_e64 v138, v139, v140, s[8:9]
	v_mul_f32_e32 v139, 0x37800000, v138
	v_cndmask_b32_e32 v138, v138, v139, vcc
	v_cmp_class_f32_e32 vcc, v3, v178
	s_mov_b64 s[8:9], 0x2400
	v_lshl_add_u64 v[152:153], v[134:135], 0, s[8:9]
	v_cndmask_b32_e32 v138, v138, v3, vcc
	v_pk_mul_f32 v[68:69], v[68:69], v[138:139] op_sel_hi:[1,0]
	v_pk_mul_f32 v[66:67], v[66:67], v[138:139] op_sel_hi:[1,0]
	v_pk_mul_f32 v[64:65], v[64:65], v[138:139] op_sel_hi:[1,0]
	v_pk_mul_f32 v[62:63], v[62:63], v[138:139] op_sel_hi:[1,0]
	v_pk_mul_f32 v[60:61], v[60:61], v[138:139] op_sel_hi:[1,0]
	v_pk_mul_f32 v[58:59], v[58:59], v[138:139] op_sel_hi:[1,0]
	v_pk_mul_f32 v[56:57], v[56:57], v[138:139] op_sel_hi:[1,0]
	v_pk_mul_f32 v[54:55], v[54:55], v[138:139] op_sel_hi:[1,0]
	s_nop 0
	s_waitcnt vmcnt(5)
	v_pk_add_f32 v[144:145], v[196:197], v[200:201]
	s_waitcnt vmcnt(4)
	v_pk_add_f32 v[140:141], v[192:193], v[204:205]
	v_pk_add_f32 v[138:139], v[190:191], v[202:203]
	v_pk_add_f32 v[142:143], v[194:195], v[198:199]
	global_load_dwordx4 v[190:193], v[208:209], off offset:3072
	global_load_dwordx4 v[194:197], v[208:209], off offset:3104
	global_load_dwordx4 v[198:201], v[208:209], off offset:3120
	global_load_dwordx4 v[202:205], v[208:209], off offset:3088
	v_mov_b32_e32 v147, v138
	v_mov_b32_e32 v146, v142
	v_mov_b32_e32 v138, v143
	v_mov_b32_e32 v142, v144
	v_mov_b32_e32 v143, v140
	v_mov_b32_e32 v140, v145
	v_pk_add_f32 v[138:139], v[146:147], v[138:139]
	v_pk_add_f32 v[140:141], v[142:143], v[140:141]
	v_lshl_add_u64 v[152:153], v[134:135], 0, s[46:47]
	v_pk_add_f32 v[138:139], v[138:139], v[140:141]
	s_nop 0
	v_pk_fma_f32 v[138:139], v[138:139], s[44:45], v[4:5] op_sel_hi:[1,0,0]
	s_nop 0
	v_div_scale_f32 v3, s[8:9], v139, v139, v138
	v_rcp_f32_e32 v140, v3
	s_nop 0
	v_fma_f32 v141, -v3, v140, 1.0
	v_fmac_f32_e32 v140, v141, v140
	v_div_scale_f32 v141, vcc, v138, v139, v138
	v_mul_f32_e32 v142, v141, v140
	v_fma_f32 v143, -v3, v142, v141
	v_fmac_f32_e32 v142, v143, v140
	v_fma_f32 v3, -v3, v142, v141
	v_div_fmas_f32 v3, v3, v140, v142
	v_div_fixup_f32 v3, v3, v139, v138
	v_cmp_gt_f32_e32 vcc, s76, v3
	v_mul_f32_e32 v138, 0x4f800000, v3
	s_nop 0
	v_cndmask_b32_e32 v3, v3, v138, vcc
	v_sqrt_f32_e32 v138, v3
	s_nop 0
	v_add_u32_e32 v139, -1, v138
	v_fma_f32 v140, -v139, v138, v3
	v_cmp_ge_f32_e64 s[8:9], 0, v140
	v_add_u32_e32 v140, 1, v138
	s_nop 0
	v_cndmask_b32_e64 v139, v138, v139, s[8:9]
	v_fma_f32 v138, -v140, v138, v3
	v_cmp_lt_f32_e64 s[8:9], 0, v138
	s_nop 1
	v_cndmask_b32_e64 v138, v139, v140, s[8:9]
	v_mul_f32_e32 v139, 0x37800000, v138
	v_cndmask_b32_e32 v138, v138, v139, vcc
	v_cmp_class_f32_e32 vcc, v3, v178
	s_nop 1
	v_cndmask_b32_e32 v138, v138, v3, vcc
	v_pk_mul_f32 v[52:53], v[52:53], v[138:139] op_sel_hi:[1,0]
	v_pk_mul_f32 v[50:51], v[50:51], v[138:139] op_sel_hi:[1,0]
	v_pk_mul_f32 v[48:49], v[48:49], v[138:139] op_sel_hi:[1,0]
	v_pk_mul_f32 v[46:47], v[46:47], v[138:139] op_sel_hi:[1,0]
	v_pk_mul_f32 v[44:45], v[44:45], v[138:139] op_sel_hi:[1,0]
	v_pk_mul_f32 v[42:43], v[42:43], v[138:139] op_sel_hi:[1,0]
	v_pk_mul_f32 v[40:41], v[40:41], v[138:139] op_sel_hi:[1,0]
	v_pk_mul_f32 v[38:39], v[38:39], v[138:139] op_sel_hi:[1,0]
	s_nop 0
	s_waitcnt vmcnt(5)
	v_pk_add_f32 v[144:145], v[162:163], v[184:185]
	s_waitcnt vmcnt(4)
	v_pk_add_f32 v[140:141], v[158:159], v[188:189]
	v_pk_add_f32 v[138:139], v[156:157], v[186:187]
	v_pk_add_f32 v[142:143], v[160:161], v[182:183]
	v_mov_b32_e32 v147, v138
	v_mov_b32_e32 v146, v142
	v_mov_b32_e32 v138, v143
	v_mov_b32_e32 v142, v144
	v_mov_b32_e32 v143, v140
	v_mov_b32_e32 v140, v145
	v_pk_add_f32 v[138:139], v[146:147], v[138:139]
	v_pk_add_f32 v[140:141], v[142:143], v[140:141]
	v_lshl_add_u64 v[146:147], v[134:135], 0, s[48:49]
	v_pk_add_f32 v[138:139], v[138:139], v[140:141]
	s_nop 0
	v_pk_fma_f32 v[138:139], v[138:139], s[44:45], v[4:5] op_sel_hi:[1,0,0]
	s_nop 0
	v_div_scale_f32 v3, s[8:9], v139, v139, v138
	v_rcp_f32_e32 v140, v3
	s_nop 0
	v_fma_f32 v141, -v3, v140, 1.0
	v_fmac_f32_e32 v140, v141, v140
	v_div_scale_f32 v141, vcc, v138, v139, v138
	v_mul_f32_e32 v142, v141, v140
	v_fma_f32 v143, -v3, v142, v141
	v_fmac_f32_e32 v142, v143, v140
	v_fma_f32 v3, -v3, v142, v141
	v_div_fmas_f32 v3, v3, v140, v142
	v_div_fixup_f32 v3, v3, v139, v138
	v_cmp_gt_f32_e32 vcc, s76, v3
	v_mul_f32_e32 v138, 0x4f800000, v3
	s_nop 0
	v_cndmask_b32_e32 v3, v3, v138, vcc
	v_sqrt_f32_e32 v138, v3
	s_nop 0
	v_add_u32_e32 v139, -1, v138
	v_fma_f32 v140, -v139, v138, v3
	v_cmp_ge_f32_e64 s[8:9], 0, v140
	v_add_u32_e32 v140, 1, v138
	s_nop 0
	v_cndmask_b32_e64 v139, v138, v139, s[8:9]
	v_fma_f32 v138, -v140, v138, v3
	v_cmp_lt_f32_e64 s[8:9], 0, v138
	s_nop 1
	v_cndmask_b32_e64 v138, v139, v140, s[8:9]
	v_mul_f32_e32 v139, 0x37800000, v138
	v_cndmask_b32_e32 v138, v138, v139, vcc
	v_cmp_class_f32_e32 vcc, v3, v178
	s_nop 1
	v_cndmask_b32_e32 v138, v138, v3, vcc
	v_pk_mul_f32 v[36:37], v[36:37], v[138:139] op_sel_hi:[1,0]
	v_pk_mul_f32 v[34:35], v[34:35], v[138:139] op_sel_hi:[1,0]
	v_pk_mul_f32 v[32:33], v[32:33], v[138:139] op_sel_hi:[1,0]
	v_pk_mul_f32 v[30:31], v[30:31], v[138:139] op_sel_hi:[1,0]
	v_pk_mul_f32 v[28:29], v[28:29], v[138:139] op_sel_hi:[1,0]
	v_pk_mul_f32 v[26:27], v[26:27], v[138:139] op_sel_hi:[1,0]
	v_pk_mul_f32 v[24:25], v[24:25], v[138:139] op_sel_hi:[1,0]
	v_pk_mul_f32 v[22:23], v[22:23], v[138:139] op_sel_hi:[1,0]
	s_nop 0
	s_nop 0
	s_waitcnt vmcnt(1)
	v_pk_add_f32 v[134:135], v[194:195], v[198:199]
	s_waitcnt vmcnt(0)
	v_pk_add_f32 v[142:143], v[190:191], v[202:203]
	v_pk_add_f32 v[144:145], v[192:193], v[204:205]
	v_pk_add_f32 v[136:137], v[196:197], v[200:201]
	v_mov_b32_e32 v138, v134
	v_mov_b32_e32 v139, v142
	v_mov_b32_e32 v142, v135
	v_pk_add_f32 v[134:135], v[138:139], v[142:143]
	v_mov_b32_e32 v138, v136
	v_mov_b32_e32 v139, v144
	v_mov_b32_e32 v144, v137
	v_pk_add_f32 v[136:137], v[138:139], v[144:145]
	s_nop 0
	v_pk_add_f32 v[134:135], v[134:135], v[136:137]
	s_nop 0
	v_pk_fma_f32 v[4:5], v[134:135], s[44:45], v[4:5] op_sel_hi:[1,0,0]
	s_nop 0
	v_div_scale_f32 v3, s[8:9], v5, v5, v4
	v_rcp_f32_e32 v134, v3
	s_nop 0
	v_fma_f32 v135, -v3, v134, 1.0
	v_fmac_f32_e32 v134, v135, v134
	v_div_scale_f32 v135, vcc, v4, v5, v4
	v_mul_f32_e32 v136, v135, v134
	v_fma_f32 v137, -v3, v136, v135
	v_fmac_f32_e32 v136, v137, v134
	v_fma_f32 v3, -v3, v136, v135
	v_div_fmas_f32 v3, v3, v134, v136
	v_div_fixup_f32 v3, v3, v5, v4
	v_cmp_gt_f32_e32 vcc, s76, v3
	v_mul_f32_e32 v4, 0x4f800000, v3
	s_nop 0
	v_cndmask_b32_e32 v3, v3, v4, vcc
	v_sqrt_f32_e32 v4, v3
	s_nop 0
	v_add_u32_e32 v5, -1, v4
	v_fma_f32 v134, -v5, v4, v3
	v_cmp_ge_f32_e64 s[8:9], 0, v134
	v_add_u32_e32 v134, 1, v4
	s_nop 0
	v_cndmask_b32_e64 v5, v4, v5, s[8:9]
	v_fma_f32 v4, -v134, v4, v3
	v_cmp_lt_f32_e64 s[8:9], 0, v4
	s_nop 1
	v_cndmask_b32_e64 v4, v5, v134, s[8:9]
	v_mul_f32_e32 v5, 0x37800000, v4
	v_cndmask_b32_e32 v4, v4, v5, vcc
	v_cmp_class_f32_e32 vcc, v3, v178
	s_nop 1
	v_cndmask_b32_e32 v4, v4, v3, vcc
	v_pk_mul_f32 v[20:21], v[20:21], v[4:5] op_sel_hi:[1,0]
	v_pk_mul_f32 v[18:19], v[18:19], v[4:5] op_sel_hi:[1,0]
	v_pk_mul_f32 v[16:17], v[16:17], v[4:5] op_sel_hi:[1,0]
	v_pk_mul_f32 v[14:15], v[14:15], v[4:5] op_sel_hi:[1,0]
	v_pk_mul_f32 v[12:13], v[12:13], v[4:5] op_sel_hi:[1,0]
	v_pk_mul_f32 v[10:11], v[10:11], v[4:5] op_sel_hi:[1,0]
	v_pk_mul_f32 v[8:9], v[8:9], v[4:5] op_sel_hi:[1,0]
	v_pk_mul_f32 v[6:7], v[6:7], v[4:5] op_sel_hi:[1,0]
	s_branch .LBB0_1880
